# grid barrier steady path hand-written: every workgroup polls the TOP arrival counter directly (no TOPGEN/XGEN relay, no division), XCD last arriver still does the L2 write-back
# speedup vs baseline: 1.0036x; 1.0036x over previous
.LBB0_63:
	s_waitcnt vmcnt(0) lgkmcnt(0)
	v_readlane_b32 s14, v254, 38
	v_readlane_b32 s15, v254, 39
	v_readlane_b32 s13, v254, 40
	v_mov_b32_e32 v0, 0x20000
	ds_read_b32 v1, v0
	ds_read_b32 v2, v0 offset:4
	s_lshl_b32 s13, s13, 8
	s_add_i32 s13, s13, 0x1400
	v_mov_b32_e32 v4, s13
	v_mov_b32_e32 v5, 1
	s_nop 3
	global_atomic_add v4, v4, v5, s[14:15] sc0
	s_waitcnt vmcnt(0) lgkmcnt(0)
	v_readfirstlane_b32 s13, v4
	v_readfirstlane_b32 s20, v1
	v_readfirstlane_b32 s16, v2
	v_mov_b32_e32 v4, 0x3400
	s_add_i32 s13, s13, 1
	s_mul_i32 s20, s20, 1
	s_mul_i32 s16, s16, 1
	s_cmp_lg_u32 s13, s20
	s_cbranch_scc1 .Lfb0_poll
	buffer_wbl2 sc1
	s_waitcnt vmcnt(0) lgkmcnt(0)
	global_atomic_add v4, v5, s[14:15]
.Lfb0_poll:
	s_mov_b32 s22, 0
.Lfb0_loop:
	global_load_dword v0, v4, s[14:15] sc1
	s_waitcnt vmcnt(0)
	v_readfirstlane_b32 s13, v0
	s_cmp_ge_u32 s13, s16
	s_cbranch_scc1 .Lfb0_done
	s_sleep 1
	s_add_i32 s22, s22, 1
	s_cmp_lt_u32 s22, 0x40000
	s_cbranch_scc1 .Lfb0_loop
.Lfb0_done:
	buffer_inv sc1
	s_waitcnt vmcnt(0)



.LBB0_670:
	s_waitcnt vmcnt(0) lgkmcnt(0)
	v_readlane_b32 s14, v254, 38
	v_readlane_b32 s15, v254, 39
	v_readlane_b32 s13, v254, 40
	v_mov_b32_e32 v0, 0x20000
	ds_read_b32 v1, v0
	ds_read_b32 v2, v0 offset:4
	s_lshl_b32 s13, s13, 8
	s_add_i32 s13, s13, 0x1400
	v_mov_b32_e32 v4, s13
	v_mov_b32_e32 v5, 1
	s_nop 3
	global_atomic_add v4, v4, v5, s[14:15] sc0
	s_waitcnt vmcnt(0) lgkmcnt(0)
	v_readfirstlane_b32 s13, v4
	v_readfirstlane_b32 s20, v1
	v_readfirstlane_b32 s16, v2
	v_mov_b32_e32 v4, 0x3400
	s_add_i32 s13, s13, 1
	s_mul_i32 s20, s20, 2
	s_mul_i32 s16, s16, 2
	s_cmp_lg_u32 s13, s20
	s_cbranch_scc1 .Lfb1_poll
	buffer_wbl2 sc1
	s_waitcnt vmcnt(0) lgkmcnt(0)
	global_atomic_add v4, v5, s[14:15]

.LBB0_969:
	s_waitcnt vmcnt(0) lgkmcnt(0)
	v_readlane_b32 s14, v254, 38
	v_readlane_b32 s15, v254, 39
	v_readlane_b32 s13, v254, 40
	v_mov_b32_e32 v0, 0x20000
	ds_read_b32 v1, v0
	ds_read_b32 v2, v0 offset:4
	s_lshl_b32 s13, s13, 8
	s_add_i32 s13, s13, 0x1400
	v_mov_b32_e32 v4, s13
	v_mov_b32_e32 v5, 1
	s_nop 3
	global_atomic_add v4, v4, v5, s[14:15] sc0
	s_waitcnt vmcnt(0) lgkmcnt(0)
	v_readfirstlane_b32 s13, v4
	v_readfirstlane_b32 s20, v1
	v_readfirstlane_b32 s16, v2
	v_mov_b32_e32 v4, 0x3400
	s_add_i32 s13, s13, 1
	s_mul_i32 s20, s20, 3
	s_mul_i32 s16, s16, 3
	s_cmp_lg_u32 s13, s20
	s_cbranch_scc1 .Lfb2_poll
	buffer_wbl2 sc1
	s_waitcnt vmcnt(0) lgkmcnt(0)
	global_atomic_add v4, v5, s[14:15]

.LBB0_1064:
	s_waitcnt vmcnt(0) lgkmcnt(0)
	v_readlane_b32 s14, v254, 38
	v_readlane_b32 s15, v254, 39
	v_readlane_b32 s13, v254, 40
	v_mov_b32_e32 v0, 0x20000
	ds_read_b32 v1, v0
	ds_read_b32 v2, v0 offset:4
	s_lshl_b32 s13, s13, 8
	s_add_i32 s13, s13, 0x1400
	v_mov_b32_e32 v4, s13
	v_mov_b32_e32 v5, 1
	s_nop 3
	global_atomic_add v4, v4, v5, s[14:15] sc0
	s_waitcnt vmcnt(0) lgkmcnt(0)
	v_readfirstlane_b32 s13, v4
	v_readfirstlane_b32 s20, v1
	v_readfirstlane_b32 s16, v2
	v_mov_b32_e32 v4, 0x3400
	s_add_i32 s13, s13, 1
	s_mul_i32 s20, s20, 4
	s_mul_i32 s16, s16, 4
	s_cmp_lg_u32 s13, s20
	s_cbranch_scc1 .Lfb3_poll
	buffer_wbl2 sc1
	s_waitcnt vmcnt(0) lgkmcnt(0)
	global_atomic_add v4, v5, s[14:15]

.LBB0_1124:
	s_waitcnt vmcnt(0) lgkmcnt(0)
	v_readlane_b32 s14, v254, 38
	v_readlane_b32 s15, v254, 39
	v_readlane_b32 s13, v254, 40
	v_mov_b32_e32 v0, 0x20000
	ds_read_b32 v1, v0
	ds_read_b32 v2, v0 offset:4
	s_lshl_b32 s13, s13, 8
	s_add_i32 s13, s13, 0x1400
	v_mov_b32_e32 v4, s13
	v_mov_b32_e32 v5, 1
	s_nop 3
	global_atomic_add v4, v4, v5, s[14:15] sc0
	s_waitcnt vmcnt(0) lgkmcnt(0)
	v_readfirstlane_b32 s13, v4
	v_readfirstlane_b32 s20, v1
	v_readfirstlane_b32 s16, v2
	v_mov_b32_e32 v4, 0x3400
	s_add_i32 s13, s13, 1
	s_mul_i32 s20, s20, 5
	s_mul_i32 s16, s16, 5
	s_cmp_lg_u32 s13, s20
	s_cbranch_scc1 .Lfb4_poll
	buffer_wbl2 sc1
	s_waitcnt vmcnt(0) lgkmcnt(0)
	global_atomic_add v4, v5, s[14:15]

.LBB0_1202:
	s_waitcnt vmcnt(0) lgkmcnt(0)
	v_readlane_b32 s14, v254, 38
	v_readlane_b32 s15, v254, 39
	v_readlane_b32 s13, v254, 40
	v_mov_b32_e32 v0, 0x20000
	ds_read_b32 v1, v0
	ds_read_b32 v2, v0 offset:4
	s_lshl_b32 s13, s13, 8
	s_add_i32 s13, s13, 0x1400
	v_mov_b32_e32 v4, s13
	v_mov_b32_e32 v5, 1
	s_nop 3
	global_atomic_add v4, v4, v5, s[14:15] sc0
	s_waitcnt vmcnt(0) lgkmcnt(0)
	v_readfirstlane_b32 s13, v4
	v_readfirstlane_b32 s20, v1
	v_readfirstlane_b32 s16, v2
	v_mov_b32_e32 v4, 0x3400
	s_add_i32 s13, s13, 1
	s_mul_i32 s20, s20, 6
	s_mul_i32 s16, s16, 6
	s_cmp_lg_u32 s13, s20
	s_cbranch_scc1 .Lfb5_poll
	buffer_wbl2 sc1
	s_waitcnt vmcnt(0) lgkmcnt(0)
	global_atomic_add v4, v5, s[14:15]

.LBB0_1294:
	s_waitcnt vmcnt(0) lgkmcnt(0)
	v_readlane_b32 s14, v254, 38
	v_readlane_b32 s15, v254, 39
	v_readlane_b32 s13, v254, 40
	v_mov_b32_e32 v0, 0x20000
	ds_read_b32 v1, v0
	ds_read_b32 v2, v0 offset:4
	s_lshl_b32 s13, s13, 8
	s_add_i32 s13, s13, 0x1400
	v_mov_b32_e32 v4, s13
	v_mov_b32_e32 v5, 1
	s_nop 3
	global_atomic_add v4, v4, v5, s[14:15] sc0
	s_waitcnt vmcnt(0) lgkmcnt(0)
	v_readfirstlane_b32 s13, v4
	v_readfirstlane_b32 s20, v1
	v_readfirstlane_b32 s16, v2
	v_mov_b32_e32 v4, 0x3400
	s_add_i32 s13, s13, 1
	s_mul_i32 s20, s20, 7
	s_mul_i32 s16, s16, 7
	s_cmp_lg_u32 s13, s20
	s_cbranch_scc1 .Lfb6_poll
	buffer_wbl2 sc1
	s_waitcnt vmcnt(0) lgkmcnt(0)
	global_atomic_add v4, v5, s[14:15]
